# GEMM LDS-DMA with SGPR base + 32-bit lane offsets (8 of 10 direct loops): per-iteration 64-bit VALU address adds replaced by scalar adds
# speedup vs baseline: 1.0082x; 1.0082x over previous
; #define MFMA32(a, b, c) __builtin_amdgcn_mfma_f32_32x32x16_bf16((a), (b), (c), 0, 0, 0)
; template <class AL, class EP>
; DI void gemm2(const int wave_s, const AL al, const u16* __restrict__ Wt, const int K, const int ntm, const int ntn, const EP ep, char* smem, const u16* zrow = nullptr) {
;     ...
;     auto stage_issue = [&](int kt, int st) {
;       char* sa = smem + st * G_STAGE_B + wv * 4096;
;       const int k0 = kt * 64;
;       if constexpr (AL::DIRECT) {
;         const u16* ab = al.tilebase(tm, k0);
; #pragma unroll
;         for (int q = 0; q < 4; ++q) {
;           const u16* gp = (aoff[q] == 0xffffffffu) ? (zrow + scp * 8) : (ab + aoff[q]);
;           glds16(gp, sa + q * 1024);
;         }
;       } else {
; #pragma unroll
;         for (int i = 0; i < 4; ++i) ra[i] = al.load(tm, lrow + 64 * i, k0, lcp * 8);
;       }
;       const u16* wb = wbase + k0;
; #pragma unroll
;       for (int q = 0; q < 4; ++q) glds16(wb + woff[q], sa + 32768 + q * 1024);
;     };
;     ...
;     for (int kt = 0; kt < nk; ++kt) {
;       const bool more = (kt + 1 < nk);
;       if (more) stage_issue(kt + 1, (kt + 1) & 1);
;       __builtin_amdgcn_sched_barrier(0);
;       const char* a = smem + (kt & 1) * G_STAGE_B + wm * 128 * 128;
;       const char* b = smem + (kt & 1) * G_STAGE_B + 32768 + wn * 64 * 128;
;       if constexpr (AL::DIRECT) {
;         bf16x8 af[2][4], bfr[2][2];
; #pragma unroll
;         for (int i = 0; i < 4; ++i) af[0][i] = *(const bf16x8*)(a + i * 4096 + foff[0]);
; #pragma unroll
;         for (int j = 0; j < 2; ++j) bfr[0][j] = *(const bf16x8*)(b + j * 4096 + foff[0]);
; #pragma unroll
;         for (int s = 0; s < 4; ++s) {
;           if (s < 3) {
; #pragma unroll
;             for (int i = 0; i < 4; ++i) af[(s + 1) & 1][i] = *(const bf16x8*)(a + i * 4096 + foff[s + 1]);
; #pragma unroll
;             for (int j = 0; j < 2; ++j) bfr[(s + 1) & 1][j] = *(const bf16x8*)(b + j * 4096 + foff[s + 1]);
;           }
;           __builtin_amdgcn_sched_barrier(0);
;           __builtin_amdgcn_s_setprio(1);
; #pragma unroll
;           for (int i = 0; i < 4; ++i) {
;             acc[i][0] = MFMA32(af[s & 1][i], bfr[s & 1][0], acc[i][0]);
;             acc[i][1] = MFMA32(af[s & 1][i], bfr[s & 1][1], acc[i][1]);
;           }
;           __builtin_amdgcn_s_setprio(0);
;           __builtin_amdgcn_sched_barrier(0);
;         }
.LBB0_1880:
	s_add_u32 s8, s10, 0x80
	s_addc_u32 s9, s11, 0
	s_add_u32 s30, s30, 0x80
	s_addc_u32 s31, s31, 0
	v_subrev_u32_e32 v176, s30, v176
	v_subrev_u32_e32 v168, s30, v168
	v_subrev_u32_e32 v166, s30, v166
	v_subrev_u32_e32 v164, s30, v164
	v_subrev_u32_e32 v162, s8, v162
	v_subrev_u32_e32 v160, s8, v160
	v_subrev_u32_e32 v158, s8, v158
	v_subrev_u32_e32 v156, s8, v156
	s_add_i32 s10, s15, 0x10000
	s_mov_b32 m0, s10
	s_nop 0
	global_load_lds_dwordx4 v176, s[30:31]
	s_add_i32 m0, s10, 0x400
	s_nop 0
	global_load_lds_dwordx4 v168, s[30:31]
	s_add_i32 m0, s10, 0x800
	s_nop 0
	global_load_lds_dwordx4 v166, s[30:31]
	s_add_i32 m0, s10, 0xc00
	s_nop 0
	global_load_lds_dwordx4 v164, s[30:31]
	s_add_i32 m0, s10, 0x8000
	s_nop 0
	global_load_lds_dwordx4 v162, s[8:9]
	s_add_i32 m0, s10, 0x8400
	s_nop 0
	global_load_lds_dwordx4 v160, s[8:9]
	s_add_i32 m0, s10, 0x8800
	s_nop 0
	global_load_lds_dwordx4 v158, s[8:9]
	s_add_i32 m0, s10, 0x8c00
	s_nop 0
	global_load_lds_dwordx4 v156, s[8:9]
	s_add_u32 s8, s8, 0x80
	s_addc_u32 s9, s9, 0
	s_add_u32 s30, s30, 0x80
	s_addc_u32 s31, s31, 0
	s_mov_b32 s10, s16
	s_mov_b32 s7, s17
	v_add_u32_e32 v0, s10, v179
	ds_read_b128 v[182:185], v0
	ds_read_b128 v[186:189], v0 offset:4096
	ds_read_b128 v[190:193], v0 offset:8192
	ds_read_b128 v[194:197], v0 offset:12288
	v_add_u32_e32 v0, s7, v179
	ds_read_b128 v[198:201], v0 offset:32768
	ds_read_b128 v[202:205], v0 offset:36864
	v_add_u32_e32 v0, s10, v178
	ds_read_b128 v[206:209], v0
	ds_read_b128 v[210:213], v0 offset:4096
	ds_read_b128 v[214:217], v0 offset:8192
	ds_read_b128 v[218:221], v0 offset:12288
	v_add_u32_e32 v0, s7, v178
	ds_read_b128 v[222:225], v0 offset:32768
	ds_read_b128 v[226:229], v0 offset:36864
.Lrot0_loop:
	s_setprio 1
	s_waitcnt lgkmcnt(6)
	v_mfma_f32_32x32x16_bf16 v[114:129], v[182:185], v[198:201], v[114:129]
	v_mfma_f32_32x32x16_bf16 v[98:113], v[182:185], v[202:205], v[98:113]
	v_mfma_f32_32x32x16_bf16 v[82:97], v[186:189], v[198:201], v[82:97]
	v_mfma_f32_32x32x16_bf16 v[66:81], v[186:189], v[202:205], v[66:81]
	v_mfma_f32_32x32x16_bf16 v[50:65], v[190:193], v[198:201], v[50:65]
	v_mfma_f32_32x32x16_bf16 v[34:49], v[190:193], v[202:205], v[34:49]
	v_mfma_f32_32x32x16_bf16 v[18:33], v[194:197], v[198:201], v[18:33]
	v_mfma_f32_32x32x16_bf16 v[2:17], v[194:197], v[202:205], v[2:17]
	s_setprio 0
	v_add_u32_e32 v0, s10, v175
	ds_read_b128 v[182:185], v0
	ds_read_b128 v[186:189], v0 offset:4096
	ds_read_b128 v[190:193], v0 offset:8192
	ds_read_b128 v[194:197], v0 offset:12288
	v_add_u32_e32 v0, s7, v175
	ds_read_b128 v[198:201], v0 offset:32768
	ds_read_b128 v[202:205], v0 offset:36864
	s_setprio 1
	s_waitcnt lgkmcnt(6)
	v_mfma_f32_32x32x16_bf16 v[114:129], v[206:209], v[222:225], v[114:129]
	v_mfma_f32_32x32x16_bf16 v[98:113], v[206:209], v[226:229], v[98:113]
	v_mfma_f32_32x32x16_bf16 v[82:97], v[210:213], v[222:225], v[82:97]
	v_mfma_f32_32x32x16_bf16 v[66:81], v[210:213], v[226:229], v[66:81]
	v_mfma_f32_32x32x16_bf16 v[50:65], v[214:217], v[222:225], v[50:65]
	v_mfma_f32_32x32x16_bf16 v[34:49], v[214:217], v[226:229], v[34:49]
	v_mfma_f32_32x32x16_bf16 v[18:33], v[218:221], v[222:225], v[18:33]
	v_mfma_f32_32x32x16_bf16 v[2:17], v[218:221], v[226:229], v[2:17]
	s_setprio 0
	v_add_u32_e32 v0, s10, v172
	ds_read_b128 v[206:209], v0
	ds_read_b128 v[210:213], v0 offset:4096
	ds_read_b128 v[214:217], v0 offset:8192
	ds_read_b128 v[218:221], v0 offset:12288
	v_add_u32_e32 v0, s7, v172
	ds_read_b128 v[222:225], v0 offset:32768
	ds_read_b128 v[226:229], v0 offset:36864
	s_add_i32 s5, s5, 0x10000
	s_and_b32 s10, s5, 0x10000
	s_add_i32 s7, s10, s17
	s_add_i32 s10, s10, s16
	s_cmp_eq_u32 s5, 0xf0000
	s_waitcnt vmcnt(0) lgkmcnt(0)
	s_barrier
	s_cbranch_scc1 .Lrot0_tail
	s_setprio 1
	s_add_i32 m0, s5, 0x10000
	s_and_b32 m0, m0, 0x10000
	s_add_i32 m0, m0, s15
	v_mfma_f32_32x32x16_bf16 v[114:129], v[182:185], v[198:201], v[114:129]
	global_load_lds_dwordx4 v176, s[30:31]
	s_add_i32 m0, m0, 0x400
	v_mfma_f32_32x32x16_bf16 v[98:113], v[182:185], v[202:205], v[98:113]
	v_mfma_f32_32x32x16_bf16 v[82:97], v[186:189], v[198:201], v[82:97]
	global_load_lds_dwordx4 v168, s[30:31]
	s_add_i32 m0, m0, 0x400
	v_mfma_f32_32x32x16_bf16 v[66:81], v[186:189], v[202:205], v[66:81]
	v_mfma_f32_32x32x16_bf16 v[50:65], v[190:193], v[198:201], v[50:65]
	global_load_lds_dwordx4 v166, s[30:31]
	s_add_i32 m0, m0, 0x400
	v_mfma_f32_32x32x16_bf16 v[34:49], v[190:193], v[202:205], v[34:49]
	v_mfma_f32_32x32x16_bf16 v[18:33], v[194:197], v[198:201], v[18:33]
	global_load_lds_dwordx4 v164, s[30:31]
	s_add_i32 m0, m0, 0x7400
	v_mfma_f32_32x32x16_bf16 v[2:17], v[194:197], v[202:205], v[2:17]
	s_setprio 0
	v_add_u32_e32 v0, s10, v179
	ds_read_b128 v[182:185], v0
	ds_read_b128 v[186:189], v0 offset:4096
	ds_read_b128 v[190:193], v0 offset:8192
	ds_read_b128 v[194:197], v0 offset:12288
	v_add_u32_e32 v0, s7, v179
	ds_read_b128 v[198:201], v0 offset:32768
	ds_read_b128 v[202:205], v0 offset:36864
	s_setprio 1
	v_mfma_f32_32x32x16_bf16 v[114:129], v[206:209], v[222:225], v[114:129]
	global_load_lds_dwordx4 v162, s[8:9]
	s_add_i32 m0, m0, 0x400
	v_mfma_f32_32x32x16_bf16 v[98:113], v[206:209], v[226:229], v[98:113]
	v_mfma_f32_32x32x16_bf16 v[82:97], v[210:213], v[222:225], v[82:97]
	global_load_lds_dwordx4 v160, s[8:9]
	s_add_i32 m0, m0, 0x400
	v_mfma_f32_32x32x16_bf16 v[66:81], v[210:213], v[226:229], v[66:81]
	v_mfma_f32_32x32x16_bf16 v[50:65], v[214:217], v[222:225], v[50:65]
	global_load_lds_dwordx4 v158, s[8:9]
	s_add_i32 m0, m0, 0x400
	v_mfma_f32_32x32x16_bf16 v[34:49], v[214:217], v[226:229], v[34:49]
	v_mfma_f32_32x32x16_bf16 v[18:33], v[218:221], v[222:225], v[18:33]
	global_load_lds_dwordx4 v156, s[8:9]
	v_mfma_f32_32x32x16_bf16 v[2:17], v[218:221], v[226:229], v[2:17]
	s_setprio 0
	v_add_u32_e32 v0, s10, v178
	ds_read_b128 v[206:209], v0
	ds_read_b128 v[210:213], v0 offset:4096
	ds_read_b128 v[214:217], v0 offset:8192
	ds_read_b128 v[218:221], v0 offset:12288
	v_add_u32_e32 v0, s7, v178
	ds_read_b128 v[222:225], v0 offset:32768
	ds_read_b128 v[226:229], v0 offset:36864
	s_add_u32 s8, s8, 0x80
	s_addc_u32 s9, s9, 0
	s_add_u32 s30, s30, 0x80
	s_addc_u32 s31, s31, 0
	s_branch .Lrot0_loop

; #define MFMA32(a, b, c) __builtin_amdgcn_mfma_f32_32x32x16_bf16((a), (b), (c), 0, 0, 0)
; template <class AL, class EP>
; DI void gemm2(const int wave_s, const AL al, const u16* __restrict__ Wt, const int K, const int ntm, const int ntn, const EP ep, char* smem, const u16* zrow = nullptr) {
;     ...
;     auto stage_issue = [&](int kt, int st) {
;       char* sa = smem + st * G_STAGE_B + wv * 4096;
;       const int k0 = kt * 64;
;       if constexpr (AL::DIRECT) {
;         const u16* ab = al.tilebase(tm, k0);
; #pragma unroll
;         for (int q = 0; q < 4; ++q) {
;           const u16* gp = (aoff[q] == 0xffffffffu) ? (zrow + scp * 8) : (ab + aoff[q]);
;           glds16(gp, sa + q * 1024);
;         }
;       } else {
; #pragma unroll
;         for (int i = 0; i < 4; ++i) ra[i] = al.load(tm, lrow + 64 * i, k0, lcp * 8);
;       }
;       const u16* wb = wbase + k0;
; #pragma unroll
;       for (int q = 0; q < 4; ++q) glds16(wb + woff[q], sa + 32768 + q * 1024);
;     ...
;     for (int kt = 0; kt < nk; ++kt) {
;       const bool more = (kt + 1 < nk);
;       if (more) stage_issue(kt + 1, (kt + 1) & 1);
;       __builtin_amdgcn_sched_barrier(0);
;       const char* a = smem + (kt & 1) * G_STAGE_B + wm * 128 * 128;
;       const char* b = smem + (kt & 1) * G_STAGE_B + 32768 + wn * 64 * 128;
;       if constexpr (AL::DIRECT) {
;         bf16x8 af[2][4], bfr[2][2];
; #pragma unroll
;         for (int i = 0; i < 4; ++i) af[0][i] = *(const bf16x8*)(a + i * 4096 + foff[0]);
; #pragma unroll
;         for (int j = 0; j < 2; ++j) bfr[0][j] = *(const bf16x8*)(b + j * 4096 + foff[0]);
; #pragma unroll
;         for (int s = 0; s < 4; ++s) {
;           if (s < 3) {
; #pragma unroll
;             for (int i = 0; i < 4; ++i) af[(s + 1) & 1][i] = *(const bf16x8*)(a + i * 4096 + foff[s + 1]);
; #pragma unroll
;             for (int j = 0; j < 2; ++j) bfr[(s + 1) & 1][j] = *(const bf16x8*)(b + j * 4096 + foff[s + 1]);
;           }
;           __builtin_amdgcn_sched_barrier(0);
;           __builtin_amdgcn_s_setprio(1);
; #pragma unroll
;           for (int i = 0; i < 4; ++i) {
;             acc[i][0] = MFMA32(af[s & 1][i], bfr[s & 1][0], acc[i][0]);
;             acc[i][1] = MFMA32(af[s & 1][i], bfr[s & 1][1], acc[i][1]);
;           }
;           __builtin_amdgcn_s_setprio(0);
;           __builtin_amdgcn_sched_barrier(0);
;         }
.LBB0_1903:
	s_add_u32 s8, s10, 0x80
	s_addc_u32 s9, s11, 0
	s_add_u32 s26, s26, 0x80
	s_addc_u32 s27, s27, 0
	v_subrev_u32_e32 v176, s26, v176
	v_subrev_u32_e32 v168, s26, v168
	v_subrev_u32_e32 v166, s26, v166
	v_subrev_u32_e32 v164, s26, v164
	v_subrev_u32_e32 v162, s8, v162
	v_subrev_u32_e32 v160, s8, v160
	v_subrev_u32_e32 v158, s8, v158
	v_subrev_u32_e32 v156, s8, v156
	s_add_i32 s10, s13, 0x10000
	s_mov_b32 m0, s10
	s_nop 0
	global_load_lds_dwordx4 v176, s[26:27]
	s_add_i32 m0, s10, 0x400
	s_nop 0
	global_load_lds_dwordx4 v168, s[26:27]
	s_add_i32 m0, s10, 0x800
	s_nop 0
	global_load_lds_dwordx4 v166, s[26:27]
	s_add_i32 m0, s10, 0xc00
	s_nop 0
	global_load_lds_dwordx4 v164, s[26:27]
	s_add_i32 m0, s10, 0x8000
	s_nop 0
	global_load_lds_dwordx4 v162, s[8:9]
	s_add_i32 m0, s10, 0x8400
	s_nop 0
	global_load_lds_dwordx4 v160, s[8:9]
	s_add_i32 m0, s10, 0x8800
	s_nop 0
	global_load_lds_dwordx4 v158, s[8:9]
	s_add_i32 m0, s10, 0x8c00
	s_nop 0
	global_load_lds_dwordx4 v156, s[8:9]
	s_add_u32 s8, s8, 0x80
	s_addc_u32 s9, s9, 0
	s_add_u32 s26, s26, 0x80
	s_addc_u32 s27, s27, 0
	s_mov_b32 s10, s14
	s_mov_b32 s7, s15
	v_add_u32_e32 v0, s10, v179
	ds_read_b128 v[182:185], v0
	ds_read_b128 v[186:189], v0 offset:4096
	ds_read_b128 v[190:193], v0 offset:8192
	ds_read_b128 v[194:197], v0 offset:12288
	v_add_u32_e32 v0, s7, v179
	ds_read_b128 v[198:201], v0 offset:32768
	ds_read_b128 v[202:205], v0 offset:36864
	v_add_u32_e32 v0, s10, v178
	ds_read_b128 v[206:209], v0
	ds_read_b128 v[210:213], v0 offset:4096
	ds_read_b128 v[214:217], v0 offset:8192
	ds_read_b128 v[218:221], v0 offset:12288
	v_add_u32_e32 v0, s7, v178
	ds_read_b128 v[222:225], v0 offset:32768
	ds_read_b128 v[226:229], v0 offset:36864
.Lrot1_loop:
	s_setprio 1
	s_waitcnt lgkmcnt(6)
	v_mfma_f32_32x32x16_bf16 v[114:129], v[182:185], v[198:201], v[114:129]
	v_mfma_f32_32x32x16_bf16 v[98:113], v[182:185], v[202:205], v[98:113]
	v_mfma_f32_32x32x16_bf16 v[82:97], v[186:189], v[198:201], v[82:97]
	v_mfma_f32_32x32x16_bf16 v[66:81], v[186:189], v[202:205], v[66:81]
	v_mfma_f32_32x32x16_bf16 v[50:65], v[190:193], v[198:201], v[50:65]
	v_mfma_f32_32x32x16_bf16 v[34:49], v[190:193], v[202:205], v[34:49]
	v_mfma_f32_32x32x16_bf16 v[18:33], v[194:197], v[198:201], v[18:33]
	v_mfma_f32_32x32x16_bf16 v[2:17], v[194:197], v[202:205], v[2:17]
	s_setprio 0
	v_add_u32_e32 v0, s10, v175
	ds_read_b128 v[182:185], v0
	ds_read_b128 v[186:189], v0 offset:4096
	ds_read_b128 v[190:193], v0 offset:8192
	ds_read_b128 v[194:197], v0 offset:12288
	v_add_u32_e32 v0, s7, v175
	ds_read_b128 v[198:201], v0 offset:32768
	ds_read_b128 v[202:205], v0 offset:36864
	s_setprio 1
	s_waitcnt lgkmcnt(6)
	v_mfma_f32_32x32x16_bf16 v[114:129], v[206:209], v[222:225], v[114:129]
	v_mfma_f32_32x32x16_bf16 v[98:113], v[206:209], v[226:229], v[98:113]
	v_mfma_f32_32x32x16_bf16 v[82:97], v[210:213], v[222:225], v[82:97]
	v_mfma_f32_32x32x16_bf16 v[66:81], v[210:213], v[226:229], v[66:81]
	v_mfma_f32_32x32x16_bf16 v[50:65], v[214:217], v[222:225], v[50:65]
	v_mfma_f32_32x32x16_bf16 v[34:49], v[214:217], v[226:229], v[34:49]
	v_mfma_f32_32x32x16_bf16 v[18:33], v[218:221], v[222:225], v[18:33]
	v_mfma_f32_32x32x16_bf16 v[2:17], v[218:221], v[226:229], v[2:17]
	s_setprio 0
	v_add_u32_e32 v0, s10, v172
	ds_read_b128 v[206:209], v0
	ds_read_b128 v[210:213], v0 offset:4096
	ds_read_b128 v[214:217], v0 offset:8192
	ds_read_b128 v[218:221], v0 offset:12288
	v_add_u32_e32 v0, s7, v172
	ds_read_b128 v[222:225], v0 offset:32768
	ds_read_b128 v[226:229], v0 offset:36864
	s_add_i32 s5, s5, 0x10000
	s_and_b32 s10, s5, 0x10000
	s_add_i32 s7, s10, s15
	s_add_i32 s10, s10, s14
	s_cmp_eq_u32 s5, 0xf0000
	s_waitcnt vmcnt(0) lgkmcnt(0)
	s_barrier
	s_cbranch_scc1 .Lrot1_tail
	s_setprio 1
	s_add_i32 m0, s5, 0x10000
	s_and_b32 m0, m0, 0x10000
	s_add_i32 m0, m0, s13
	v_mfma_f32_32x32x16_bf16 v[114:129], v[182:185], v[198:201], v[114:129]
	global_load_lds_dwordx4 v176, s[26:27]
	s_add_i32 m0, m0, 0x400
	v_mfma_f32_32x32x16_bf16 v[98:113], v[182:185], v[202:205], v[98:113]
	v_mfma_f32_32x32x16_bf16 v[82:97], v[186:189], v[198:201], v[82:97]
	global_load_lds_dwordx4 v168, s[26:27]
	s_add_i32 m0, m0, 0x400
	v_mfma_f32_32x32x16_bf16 v[66:81], v[186:189], v[202:205], v[66:81]
	v_mfma_f32_32x32x16_bf16 v[50:65], v[190:193], v[198:201], v[50:65]
	global_load_lds_dwordx4 v166, s[26:27]
	s_add_i32 m0, m0, 0x400
	v_mfma_f32_32x32x16_bf16 v[34:49], v[190:193], v[202:205], v[34:49]
	v_mfma_f32_32x32x16_bf16 v[18:33], v[194:197], v[198:201], v[18:33]
	global_load_lds_dwordx4 v164, s[26:27]
	s_add_i32 m0, m0, 0x7400
	v_mfma_f32_32x32x16_bf16 v[2:17], v[194:197], v[202:205], v[2:17]
	s_setprio 0
	v_add_u32_e32 v0, s10, v179
	ds_read_b128 v[182:185], v0
	ds_read_b128 v[186:189], v0 offset:4096
	ds_read_b128 v[190:193], v0 offset:8192
	ds_read_b128 v[194:197], v0 offset:12288
	v_add_u32_e32 v0, s7, v179
	ds_read_b128 v[198:201], v0 offset:32768
	ds_read_b128 v[202:205], v0 offset:36864
	s_setprio 1
	v_mfma_f32_32x32x16_bf16 v[114:129], v[206:209], v[222:225], v[114:129]
	global_load_lds_dwordx4 v162, s[8:9]
	s_add_i32 m0, m0, 0x400
	v_mfma_f32_32x32x16_bf16 v[98:113], v[206:209], v[226:229], v[98:113]
	v_mfma_f32_32x32x16_bf16 v[82:97], v[210:213], v[222:225], v[82:97]
	global_load_lds_dwordx4 v160, s[8:9]
	s_add_i32 m0, m0, 0x400
	v_mfma_f32_32x32x16_bf16 v[66:81], v[210:213], v[226:229], v[66:81]
	v_mfma_f32_32x32x16_bf16 v[50:65], v[214:217], v[222:225], v[50:65]
	global_load_lds_dwordx4 v158, s[8:9]
	s_add_i32 m0, m0, 0x400
	v_mfma_f32_32x32x16_bf16 v[34:49], v[214:217], v[226:229], v[34:49]
	v_mfma_f32_32x32x16_bf16 v[18:33], v[218:221], v[222:225], v[18:33]
	global_load_lds_dwordx4 v156, s[8:9]
	v_mfma_f32_32x32x16_bf16 v[2:17], v[218:221], v[226:229], v[2:17]
	s_setprio 0
	v_add_u32_e32 v0, s10, v178
	ds_read_b128 v[206:209], v0
	ds_read_b128 v[210:213], v0 offset:4096
	ds_read_b128 v[214:217], v0 offset:8192
	ds_read_b128 v[218:221], v0 offset:12288
	v_add_u32_e32 v0, s7, v178
	ds_read_b128 v[222:225], v0 offset:32768
	ds_read_b128 v[226:229], v0 offset:36864
	s_add_u32 s8, s8, 0x80
	s_addc_u32 s9, s9, 0
	s_add_u32 s26, s26, 0x80
	s_addc_u32 s27, s27, 0
	s_branch .Lrot1_loop

; #define MFMA32(a, b, c) __builtin_amdgcn_mfma_f32_32x32x16_bf16((a), (b), (c), 0, 0, 0)
; template <class AL, class EP>
; DI void gemm2(const int wave_s, const AL al, const u16* __restrict__ Wt, const int K, const int ntm, const int ntn, const EP ep, char* smem, const u16* zrow = nullptr) {
;     ...
;     auto stage_issue = [&](int kt, int st) {
;       char* sa = smem + st * G_STAGE_B + wv * 4096;
;       const int k0 = kt * 64;
;       if constexpr (AL::DIRECT) {
;         const u16* ab = al.tilebase(tm, k0);
; #pragma unroll
;         for (int q = 0; q < 4; ++q) {
;           const u16* gp = (aoff[q] == 0xffffffffu) ? (zrow + scp * 8) : (ab + aoff[q]);
;           glds16(gp, sa + q * 1024);
;         }
;       } else {
; #pragma unroll
;         for (int i = 0; i < 4; ++i) ra[i] = al.load(tm, lrow + 64 * i, k0, lcp * 8);
;       }
;       const u16* wb = wbase + k0;
; #pragma unroll
;       for (int q = 0; q < 4; ++q) glds16(wb + woff[q], sa + 32768 + q * 1024);
;     ...
;     for (int kt = 0; kt < nk; ++kt) {
;       const bool more = (kt + 1 < nk);
;       if (more) stage_issue(kt + 1, (kt + 1) & 1);
;       __builtin_amdgcn_sched_barrier(0);
;       const char* a = smem + (kt & 1) * G_STAGE_B + wm * 128 * 128;
;       const char* b = smem + (kt & 1) * G_STAGE_B + 32768 + wn * 64 * 128;
;       if constexpr (AL::DIRECT) {
;         bf16x8 af[2][4], bfr[2][2];
; #pragma unroll
;         for (int i = 0; i < 4; ++i) af[0][i] = *(const bf16x8*)(a + i * 4096 + foff[0]);
; #pragma unroll
;         for (int j = 0; j < 2; ++j) bfr[0][j] = *(const bf16x8*)(b + j * 4096 + foff[0]);
; #pragma unroll
;         for (int s = 0; s < 4; ++s) {
;           if (s < 3) {
; #pragma unroll
;             for (int i = 0; i < 4; ++i) af[(s + 1) & 1][i] = *(const bf16x8*)(a + i * 4096 + foff[s + 1]);
; #pragma unroll
;             for (int j = 0; j < 2; ++j) bfr[(s + 1) & 1][j] = *(const bf16x8*)(b + j * 4096 + foff[s + 1]);
;           }
;           __builtin_amdgcn_sched_barrier(0);
;           __builtin_amdgcn_s_setprio(1);
; #pragma unroll
;           for (int i = 0; i < 4; ++i) {
;             acc[i][0] = MFMA32(af[s & 1][i], bfr[s & 1][0], acc[i][0]);
;             acc[i][1] = MFMA32(af[s & 1][i], bfr[s & 1][1], acc[i][1]);
;           }
;           __builtin_amdgcn_s_setprio(0);
;           __builtin_amdgcn_sched_barrier(0);
;         }
.LBB0_2473:
	s_add_u32 s8, s10, 0x80
	s_addc_u32 s9, s11, 0
	s_add_u32 s28, s28, 0x80
	s_addc_u32 s29, s29, 0
	v_subrev_u32_e32 v176, s28, v176
	v_subrev_u32_e32 v168, s28, v168
	v_subrev_u32_e32 v166, s28, v166
	v_subrev_u32_e32 v164, s28, v164
	v_subrev_u32_e32 v162, s8, v162
	v_subrev_u32_e32 v160, s8, v160
	v_subrev_u32_e32 v158, s8, v158
	v_subrev_u32_e32 v156, s8, v156
	s_add_i32 s10, s15, 0x10000
	s_mov_b32 m0, s10
	s_nop 0
	global_load_lds_dwordx4 v176, s[28:29]
	s_add_i32 m0, s10, 0x400
	s_nop 0
	global_load_lds_dwordx4 v168, s[28:29]
	s_add_i32 m0, s10, 0x800
	s_nop 0
	global_load_lds_dwordx4 v166, s[28:29]
	s_add_i32 m0, s10, 0xc00
	s_nop 0
	global_load_lds_dwordx4 v164, s[28:29]
	s_add_i32 m0, s10, 0x8000
	s_nop 0
	global_load_lds_dwordx4 v162, s[8:9]
	s_add_i32 m0, s10, 0x8400
	s_nop 0
	global_load_lds_dwordx4 v160, s[8:9]
	s_add_i32 m0, s10, 0x8800
	s_nop 0
	global_load_lds_dwordx4 v158, s[8:9]
	s_add_i32 m0, s10, 0x8c00
	s_nop 0
	global_load_lds_dwordx4 v156, s[8:9]
	s_add_u32 s8, s8, 0x80
	s_addc_u32 s9, s9, 0
	s_add_u32 s28, s28, 0x80
	s_addc_u32 s29, s29, 0
	s_mov_b32 s10, s16
	s_mov_b32 s7, s17
	v_add_u32_e32 v0, s10, v179
	ds_read_b128 v[182:185], v0
	ds_read_b128 v[186:189], v0 offset:4096
	ds_read_b128 v[190:193], v0 offset:8192
	ds_read_b128 v[194:197], v0 offset:12288
	v_add_u32_e32 v0, s7, v179
	ds_read_b128 v[198:201], v0 offset:32768
	ds_read_b128 v[202:205], v0 offset:36864
	v_add_u32_e32 v0, s10, v178
	ds_read_b128 v[206:209], v0
	ds_read_b128 v[210:213], v0 offset:4096
	ds_read_b128 v[214:217], v0 offset:8192
	ds_read_b128 v[218:221], v0 offset:12288
	v_add_u32_e32 v0, s7, v178
	ds_read_b128 v[222:225], v0 offset:32768
	ds_read_b128 v[226:229], v0 offset:36864
.Lrot2_loop:
	s_setprio 1
	s_waitcnt lgkmcnt(6)
	v_mfma_f32_32x32x16_bf16 v[114:129], v[182:185], v[198:201], v[114:129]
	v_mfma_f32_32x32x16_bf16 v[98:113], v[182:185], v[202:205], v[98:113]
	v_mfma_f32_32x32x16_bf16 v[82:97], v[186:189], v[198:201], v[82:97]
	v_mfma_f32_32x32x16_bf16 v[66:81], v[186:189], v[202:205], v[66:81]
	v_mfma_f32_32x32x16_bf16 v[50:65], v[190:193], v[198:201], v[50:65]
	v_mfma_f32_32x32x16_bf16 v[34:49], v[190:193], v[202:205], v[34:49]
	v_mfma_f32_32x32x16_bf16 v[18:33], v[194:197], v[198:201], v[18:33]
	v_mfma_f32_32x32x16_bf16 v[2:17], v[194:197], v[202:205], v[2:17]
	s_setprio 0
	v_add_u32_e32 v0, s10, v175
	ds_read_b128 v[182:185], v0
	ds_read_b128 v[186:189], v0 offset:4096
	ds_read_b128 v[190:193], v0 offset:8192
	ds_read_b128 v[194:197], v0 offset:12288
	v_add_u32_e32 v0, s7, v175
	ds_read_b128 v[198:201], v0 offset:32768
	ds_read_b128 v[202:205], v0 offset:36864
	s_setprio 1
	s_waitcnt lgkmcnt(6)
	v_mfma_f32_32x32x16_bf16 v[114:129], v[206:209], v[222:225], v[114:129]
	v_mfma_f32_32x32x16_bf16 v[98:113], v[206:209], v[226:229], v[98:113]
	v_mfma_f32_32x32x16_bf16 v[82:97], v[210:213], v[222:225], v[82:97]
	v_mfma_f32_32x32x16_bf16 v[66:81], v[210:213], v[226:229], v[66:81]
	v_mfma_f32_32x32x16_bf16 v[50:65], v[214:217], v[222:225], v[50:65]
	v_mfma_f32_32x32x16_bf16 v[34:49], v[214:217], v[226:229], v[34:49]
	v_mfma_f32_32x32x16_bf16 v[18:33], v[218:221], v[222:225], v[18:33]
	v_mfma_f32_32x32x16_bf16 v[2:17], v[218:221], v[226:229], v[2:17]
	s_setprio 0
	v_add_u32_e32 v0, s10, v172
	ds_read_b128 v[206:209], v0
	ds_read_b128 v[210:213], v0 offset:4096
	ds_read_b128 v[214:217], v0 offset:8192
	ds_read_b128 v[218:221], v0 offset:12288
	v_add_u32_e32 v0, s7, v172
	ds_read_b128 v[222:225], v0 offset:32768
	ds_read_b128 v[226:229], v0 offset:36864
	s_add_i32 s5, s5, 0x10000
	s_and_b32 s10, s5, 0x10000
	s_add_i32 s7, s10, s17
	s_add_i32 s10, s10, s16
	s_cmp_eq_u32 s5, 0xf0000
	s_waitcnt vmcnt(0) lgkmcnt(0)
	s_barrier
	s_cbranch_scc1 .Lrot2_tail
	s_setprio 1
	s_add_i32 m0, s5, 0x10000
	s_and_b32 m0, m0, 0x10000
	s_add_i32 m0, m0, s15
	v_mfma_f32_32x32x16_bf16 v[114:129], v[182:185], v[198:201], v[114:129]
	global_load_lds_dwordx4 v176, s[28:29]
	s_add_i32 m0, m0, 0x400
	v_mfma_f32_32x32x16_bf16 v[98:113], v[182:185], v[202:205], v[98:113]
	v_mfma_f32_32x32x16_bf16 v[82:97], v[186:189], v[198:201], v[82:97]
	global_load_lds_dwordx4 v168, s[28:29]
	s_add_i32 m0, m0, 0x400
	v_mfma_f32_32x32x16_bf16 v[66:81], v[186:189], v[202:205], v[66:81]
	v_mfma_f32_32x32x16_bf16 v[50:65], v[190:193], v[198:201], v[50:65]
	global_load_lds_dwordx4 v166, s[28:29]
	s_add_i32 m0, m0, 0x400
	v_mfma_f32_32x32x16_bf16 v[34:49], v[190:193], v[202:205], v[34:49]
	v_mfma_f32_32x32x16_bf16 v[18:33], v[194:197], v[198:201], v[18:33]
	global_load_lds_dwordx4 v164, s[28:29]
	s_add_i32 m0, m0, 0x7400
	v_mfma_f32_32x32x16_bf16 v[2:17], v[194:197], v[202:205], v[2:17]
	s_setprio 0
	v_add_u32_e32 v0, s10, v179
	ds_read_b128 v[182:185], v0
	ds_read_b128 v[186:189], v0 offset:4096
	ds_read_b128 v[190:193], v0 offset:8192
	ds_read_b128 v[194:197], v0 offset:12288
	v_add_u32_e32 v0, s7, v179
	ds_read_b128 v[198:201], v0 offset:32768
	ds_read_b128 v[202:205], v0 offset:36864
	s_setprio 1
	v_mfma_f32_32x32x16_bf16 v[114:129], v[206:209], v[222:225], v[114:129]
	global_load_lds_dwordx4 v162, s[8:9]
	s_add_i32 m0, m0, 0x400
	v_mfma_f32_32x32x16_bf16 v[98:113], v[206:209], v[226:229], v[98:113]
	v_mfma_f32_32x32x16_bf16 v[82:97], v[210:213], v[222:225], v[82:97]
	global_load_lds_dwordx4 v160, s[8:9]
	s_add_i32 m0, m0, 0x400
	v_mfma_f32_32x32x16_bf16 v[66:81], v[210:213], v[226:229], v[66:81]
	v_mfma_f32_32x32x16_bf16 v[50:65], v[214:217], v[222:225], v[50:65]
	global_load_lds_dwordx4 v158, s[8:9]
	s_add_i32 m0, m0, 0x400
	v_mfma_f32_32x32x16_bf16 v[34:49], v[214:217], v[226:229], v[34:49]
	v_mfma_f32_32x32x16_bf16 v[18:33], v[218:221], v[222:225], v[18:33]
	global_load_lds_dwordx4 v156, s[8:9]
	v_mfma_f32_32x32x16_bf16 v[2:17], v[218:221], v[226:229], v[2:17]
	s_setprio 0
	v_add_u32_e32 v0, s10, v178
	ds_read_b128 v[206:209], v0
	ds_read_b128 v[210:213], v0 offset:4096
	ds_read_b128 v[214:217], v0 offset:8192
	ds_read_b128 v[218:221], v0 offset:12288
	v_add_u32_e32 v0, s7, v178
	ds_read_b128 v[222:225], v0 offset:32768
	ds_read_b128 v[226:229], v0 offset:36864
	s_add_u32 s8, s8, 0x80
	s_addc_u32 s9, s9, 0
	s_add_u32 s28, s28, 0x80
	s_addc_u32 s29, s29, 0
	s_branch .Lrot2_loop

; #define MFMA32(a, b, c) __builtin_amdgcn_mfma_f32_32x32x16_bf16((a), (b), (c), 0, 0, 0)
; template <class AL, class EP>
; DI void gemm2(const int wave_s, const AL al, const u16* __restrict__ Wt, const int K, const int ntm, const int ntn, const EP ep, char* smem, const u16* zrow = nullptr) {
;     ...
;     auto stage_issue = [&](int kt, int st) {
;       char* sa = smem + st * G_STAGE_B + wv * 4096;
;       const int k0 = kt * 64;
;       if constexpr (AL::DIRECT) {
;         const u16* ab = al.tilebase(tm, k0);
; #pragma unroll
;         for (int q = 0; q < 4; ++q) {
;           const u16* gp = (aoff[q] == 0xffffffffu) ? (zrow + scp * 8) : (ab + aoff[q]);
;           glds16(gp, sa + q * 1024);
;         }
;       } else {
; #pragma unroll
;         for (int i = 0; i < 4; ++i) ra[i] = al.load(tm, lrow + 64 * i, k0, lcp * 8);
;       }
;       const u16* wb = wbase + k0;
; #pragma unroll
;       for (int q = 0; q < 4; ++q) glds16(wb + woff[q], sa + 32768 + q * 1024);
;     ...
;     for (int kt = 0; kt < nk; ++kt) {
;       const bool more = (kt + 1 < nk);
;       if (more) stage_issue(kt + 1, (kt + 1) & 1);
;       __builtin_amdgcn_sched_barrier(0);
;       const char* a = smem + (kt & 1) * G_STAGE_B + wm * 128 * 128;
;       const char* b = smem + (kt & 1) * G_STAGE_B + 32768 + wn * 64 * 128;
;       if constexpr (AL::DIRECT) {
;         bf16x8 af[2][4], bfr[2][2];
; #pragma unroll
;         for (int i = 0; i < 4; ++i) af[0][i] = *(const bf16x8*)(a + i * 4096 + foff[0]);
; #pragma unroll
;         for (int j = 0; j < 2; ++j) bfr[0][j] = *(const bf16x8*)(b + j * 4096 + foff[0]);
; #pragma unroll
;         for (int s = 0; s < 4; ++s) {
;           if (s < 3) {
; #pragma unroll
;             for (int i = 0; i < 4; ++i) af[(s + 1) & 1][i] = *(const bf16x8*)(a + i * 4096 + foff[s + 1]);
; #pragma unroll
;             for (int j = 0; j < 2; ++j) bfr[(s + 1) & 1][j] = *(const bf16x8*)(b + j * 4096 + foff[s + 1]);
;           }
;           __builtin_amdgcn_sched_barrier(0);
;           __builtin_amdgcn_s_setprio(1);
; #pragma unroll
;           for (int i = 0; i < 4; ++i) {
;             acc[i][0] = MFMA32(af[s & 1][i], bfr[s & 1][0], acc[i][0]);
;             acc[i][1] = MFMA32(af[s & 1][i], bfr[s & 1][1], acc[i][1]);
;           }
;           __builtin_amdgcn_s_setprio(0);
;           __builtin_amdgcn_sched_barrier(0);
;         }
.LBB0_2496:
	s_add_u32 s8, s10, 0x80
	s_addc_u32 s9, s11, 0
	s_add_u32 s14, s14, 0x80
	s_addc_u32 s15, s15, 0
	v_subrev_u32_e32 v180, s14, v180
	v_subrev_u32_e32 v178, s14, v178
	v_subrev_u32_e32 v176, s14, v176
	v_subrev_u32_e32 v168, s14, v168
	v_subrev_u32_e32 v166, s8, v166
	v_subrev_u32_e32 v164, s8, v164
	v_subrev_u32_e32 v162, s8, v162
	v_subrev_u32_e32 v160, s8, v160
	s_add_i32 s10, s25, 0x10000
	s_mov_b32 m0, s10
	s_nop 0
	global_load_lds_dwordx4 v180, s[14:15]
	s_add_i32 m0, s10, 0x400
	s_nop 0
	global_load_lds_dwordx4 v178, s[14:15]
	s_add_i32 m0, s10, 0x800
	s_nop 0
	global_load_lds_dwordx4 v176, s[14:15]
	s_add_i32 m0, s10, 0xc00
	s_nop 0
	global_load_lds_dwordx4 v168, s[14:15]
	s_add_i32 m0, s10, 0x8000
	s_nop 0
	global_load_lds_dwordx4 v166, s[8:9]
	s_add_i32 m0, s10, 0x8400
	s_nop 0
	global_load_lds_dwordx4 v164, s[8:9]
	s_add_i32 m0, s10, 0x8800
	s_nop 0
	global_load_lds_dwordx4 v162, s[8:9]
	s_add_i32 m0, s10, 0x8c00
	s_nop 0
	global_load_lds_dwordx4 v160, s[8:9]
	s_add_u32 s8, s8, 0x80
	s_addc_u32 s9, s9, 0
	s_add_u32 s14, s14, 0x80
	s_addc_u32 s15, s15, 0
	s_mov_b32 s10, s26
	s_mov_b32 s7, s27
	v_add_u32_e32 v185, s10, v183
	ds_read_b128 v[186:189], v185
	ds_read_b128 v[190:193], v185 offset:4096
	ds_read_b128 v[194:197], v185 offset:8192
	ds_read_b128 v[198:201], v185 offset:12288
	v_add_u32_e32 v185, s7, v183
	ds_read_b128 v[202:205], v185 offset:32768
	ds_read_b128 v[206:209], v185 offset:36864
	v_add_u32_e32 v185, s10, v182
	ds_read_b128 v[210:213], v185
	ds_read_b128 v[214:217], v185 offset:4096
	ds_read_b128 v[218:221], v185 offset:8192
	ds_read_b128 v[222:225], v185 offset:12288
	v_add_u32_e32 v185, s7, v182
	ds_read_b128 v[226:229], v185 offset:32768
	ds_read_b128 v[250:253], v185 offset:36864
.Lrot3_loop:
	s_setprio 1
	s_waitcnt lgkmcnt(6)
	v_mfma_f32_32x32x16_bf16 v[114:129], v[186:189], v[202:205], v[114:129]
	v_mfma_f32_32x32x16_bf16 v[98:113], v[186:189], v[206:209], v[98:113]
	v_mfma_f32_32x32x16_bf16 v[82:97], v[190:193], v[202:205], v[82:97]
	v_mfma_f32_32x32x16_bf16 v[66:81], v[190:193], v[206:209], v[66:81]
	v_mfma_f32_32x32x16_bf16 v[50:65], v[194:197], v[202:205], v[50:65]
	v_mfma_f32_32x32x16_bf16 v[34:49], v[194:197], v[206:209], v[34:49]
	v_mfma_f32_32x32x16_bf16 v[18:33], v[198:201], v[202:205], v[18:33]
	v_mfma_f32_32x32x16_bf16 v[2:17], v[198:201], v[206:209], v[2:17]
	s_setprio 0
	v_add_u32_e32 v185, s10, v175
	ds_read_b128 v[186:189], v185
	ds_read_b128 v[190:193], v185 offset:4096
	ds_read_b128 v[194:197], v185 offset:8192
	ds_read_b128 v[198:201], v185 offset:12288
	v_add_u32_e32 v185, s7, v175
	ds_read_b128 v[202:205], v185 offset:32768
	ds_read_b128 v[206:209], v185 offset:36864
	s_setprio 1
	s_waitcnt lgkmcnt(6)
	v_mfma_f32_32x32x16_bf16 v[114:129], v[210:213], v[226:229], v[114:129]
	v_mfma_f32_32x32x16_bf16 v[98:113], v[210:213], v[250:253], v[98:113]
	v_mfma_f32_32x32x16_bf16 v[82:97], v[214:217], v[226:229], v[82:97]
	v_mfma_f32_32x32x16_bf16 v[66:81], v[214:217], v[250:253], v[66:81]
	v_mfma_f32_32x32x16_bf16 v[50:65], v[218:221], v[226:229], v[50:65]
	v_mfma_f32_32x32x16_bf16 v[34:49], v[218:221], v[250:253], v[34:49]
	v_mfma_f32_32x32x16_bf16 v[18:33], v[222:225], v[226:229], v[18:33]
	v_mfma_f32_32x32x16_bf16 v[2:17], v[222:225], v[250:253], v[2:17]
	s_setprio 0
	v_add_u32_e32 v185, s10, v172
	ds_read_b128 v[210:213], v185
	ds_read_b128 v[214:217], v185 offset:4096
	ds_read_b128 v[218:221], v185 offset:8192
	ds_read_b128 v[222:225], v185 offset:12288
	v_add_u32_e32 v185, s7, v172
	ds_read_b128 v[226:229], v185 offset:32768
	ds_read_b128 v[250:253], v185 offset:36864
	s_add_i32 s5, s5, 0x10000
	s_and_b32 s10, s5, 0x10000
	s_add_i32 s7, s10, s27
	s_add_i32 s10, s10, s26
	s_cmp_eq_u32 s5, 0xf0000
	s_waitcnt vmcnt(0) lgkmcnt(0)
	s_barrier
	s_cbranch_scc1 .Lrot3_tail
	s_setprio 1
	s_add_i32 m0, s5, 0x10000
	s_and_b32 m0, m0, 0x10000
	s_add_i32 m0, m0, s25
	v_mfma_f32_32x32x16_bf16 v[114:129], v[186:189], v[202:205], v[114:129]
	global_load_lds_dwordx4 v180, s[14:15]
	s_add_i32 m0, m0, 0x400
	v_mfma_f32_32x32x16_bf16 v[98:113], v[186:189], v[206:209], v[98:113]
	v_mfma_f32_32x32x16_bf16 v[82:97], v[190:193], v[202:205], v[82:97]
	global_load_lds_dwordx4 v178, s[14:15]
	s_add_i32 m0, m0, 0x400
	v_mfma_f32_32x32x16_bf16 v[66:81], v[190:193], v[206:209], v[66:81]
	v_mfma_f32_32x32x16_bf16 v[50:65], v[194:197], v[202:205], v[50:65]
	global_load_lds_dwordx4 v176, s[14:15]
	s_add_i32 m0, m0, 0x400
	v_mfma_f32_32x32x16_bf16 v[34:49], v[194:197], v[206:209], v[34:49]
	v_mfma_f32_32x32x16_bf16 v[18:33], v[198:201], v[202:205], v[18:33]
	global_load_lds_dwordx4 v168, s[14:15]
	s_add_i32 m0, m0, 0x7400
	v_mfma_f32_32x32x16_bf16 v[2:17], v[198:201], v[206:209], v[2:17]
	s_setprio 0
	v_add_u32_e32 v185, s10, v183
	ds_read_b128 v[186:189], v185
	ds_read_b128 v[190:193], v185 offset:4096
	ds_read_b128 v[194:197], v185 offset:8192
	ds_read_b128 v[198:201], v185 offset:12288
	v_add_u32_e32 v185, s7, v183
	ds_read_b128 v[202:205], v185 offset:32768
	ds_read_b128 v[206:209], v185 offset:36864
	s_setprio 1
	v_mfma_f32_32x32x16_bf16 v[114:129], v[210:213], v[226:229], v[114:129]
	global_load_lds_dwordx4 v166, s[8:9]
	s_add_i32 m0, m0, 0x400
	v_mfma_f32_32x32x16_bf16 v[98:113], v[210:213], v[250:253], v[98:113]
	v_mfma_f32_32x32x16_bf16 v[82:97], v[214:217], v[226:229], v[82:97]
	global_load_lds_dwordx4 v164, s[8:9]
	s_add_i32 m0, m0, 0x400
	v_mfma_f32_32x32x16_bf16 v[66:81], v[214:217], v[250:253], v[66:81]
	v_mfma_f32_32x32x16_bf16 v[50:65], v[218:221], v[226:229], v[50:65]
	global_load_lds_dwordx4 v162, s[8:9]
	s_add_i32 m0, m0, 0x400
	v_mfma_f32_32x32x16_bf16 v[34:49], v[218:221], v[250:253], v[34:49]
	v_mfma_f32_32x32x16_bf16 v[18:33], v[222:225], v[226:229], v[18:33]
	global_load_lds_dwordx4 v160, s[8:9]
	v_mfma_f32_32x32x16_bf16 v[2:17], v[222:225], v[250:253], v[2:17]
	s_setprio 0
	v_add_u32_e32 v185, s10, v182
	ds_read_b128 v[210:213], v185
	ds_read_b128 v[214:217], v185 offset:4096
	ds_read_b128 v[218:221], v185 offset:8192
	ds_read_b128 v[222:225], v185 offset:12288
	v_add_u32_e32 v185, s7, v182
	ds_read_b128 v[226:229], v185 offset:32768
	ds_read_b128 v[250:253], v185 offset:36864
	s_add_u32 s8, s8, 0x80
	s_addc_u32 s9, s9, 0
	s_add_u32 s14, s14, 0x80
	s_addc_u32 s15, s15, 0
	s_branch .Lrot3_loop

; #define MFMA32(a, b, c) __builtin_amdgcn_mfma_f32_32x32x16_bf16((a), (b), (c), 0, 0, 0)
; template <class AL, class EP>
; DI void gemm2(const int wave_s, const AL al, const u16* __restrict__ Wt, const int K, const int ntm, const int ntn, const EP ep, char* smem, const u16* zrow = nullptr) {
;     ...
;     auto stage_issue = [&](int kt, int st) {
;       char* sa = smem + st * G_STAGE_B + wv * 4096;
;       const int k0 = kt * 64;
;       if constexpr (AL::DIRECT) {
;         const u16* ab = al.tilebase(tm, k0);
; #pragma unroll
;         for (int q = 0; q < 4; ++q) {
;           const u16* gp = (aoff[q] == 0xffffffffu) ? (zrow + scp * 8) : (ab + aoff[q]);
;           glds16(gp, sa + q * 1024);
;         }
;       } else {
; #pragma unroll
;         for (int i = 0; i < 4; ++i) ra[i] = al.load(tm, lrow + 64 * i, k0, lcp * 8);
;       }
;       const u16* wb = wbase + k0;
; #pragma unroll
;       for (int q = 0; q < 4; ++q) glds16(wb + woff[q], sa + 32768 + q * 1024);
;     ...
;     for (int kt = 0; kt < nk; ++kt) {
;       const bool more = (kt + 1 < nk);
;       if (more) stage_issue(kt + 1, (kt + 1) & 1);
;       __builtin_amdgcn_sched_barrier(0);
;       const char* a = smem + (kt & 1) * G_STAGE_B + wm * 128 * 128;
;       const char* b = smem + (kt & 1) * G_STAGE_B + 32768 + wn * 64 * 128;
;       if constexpr (AL::DIRECT) {
;         bf16x8 af[2][4], bfr[2][2];
; #pragma unroll
;         for (int i = 0; i < 4; ++i) af[0][i] = *(const bf16x8*)(a + i * 4096 + foff[0]);
; #pragma unroll
;         for (int j = 0; j < 2; ++j) bfr[0][j] = *(const bf16x8*)(b + j * 4096 + foff[0]);
; #pragma unroll
;         for (int s = 0; s < 4; ++s) {
;           if (s < 3) {
; #pragma unroll
;             for (int i = 0; i < 4; ++i) af[(s + 1) & 1][i] = *(const bf16x8*)(a + i * 4096 + foff[s + 1]);
; #pragma unroll
;             for (int j = 0; j < 2; ++j) bfr[(s + 1) & 1][j] = *(const bf16x8*)(b + j * 4096 + foff[s + 1]);
;           }
;           __builtin_amdgcn_sched_barrier(0);
;           __builtin_amdgcn_s_setprio(1);
; #pragma unroll
;           for (int i = 0; i < 4; ++i) {
;             acc[i][0] = MFMA32(af[s & 1][i], bfr[s & 1][0], acc[i][0]);
;             acc[i][1] = MFMA32(af[s & 1][i], bfr[s & 1][1], acc[i][1]);
;           }
;           __builtin_amdgcn_s_setprio(0);
;           __builtin_amdgcn_sched_barrier(0);
;         }
.LBB0_2878:
	s_add_u32 s12, s14, 0x80
	s_addc_u32 s13, s15, 0
	s_add_u32 s18, s18, 0x80
	s_addc_u32 s19, s19, 0
	v_subrev_u32_e32 v180, s18, v180
	v_subrev_u32_e32 v178, s18, v178
	v_subrev_u32_e32 v176, s18, v176
	v_subrev_u32_e32 v168, s18, v168
	v_subrev_u32_e32 v166, s12, v166
	v_subrev_u32_e32 v164, s12, v164
	v_subrev_u32_e32 v162, s12, v162
	v_subrev_u32_e32 v160, s12, v160
	s_add_i32 s14, s27, 0x10000
	s_mov_b32 m0, s14
	s_nop 0
	global_load_lds_dwordx4 v180, s[18:19]
	s_add_i32 m0, s14, 0x400
	s_nop 0
	global_load_lds_dwordx4 v178, s[18:19]
	s_add_i32 m0, s14, 0x800
	s_nop 0
	global_load_lds_dwordx4 v176, s[18:19]
	s_add_i32 m0, s14, 0xc00
	s_nop 0
	global_load_lds_dwordx4 v168, s[18:19]
	s_add_i32 m0, s14, 0x8000
	s_nop 0
	global_load_lds_dwordx4 v166, s[12:13]
	s_add_i32 m0, s14, 0x8400
	s_nop 0
	global_load_lds_dwordx4 v164, s[12:13]
	s_add_i32 m0, s14, 0x8800
	s_nop 0
	global_load_lds_dwordx4 v162, s[12:13]
	s_add_i32 m0, s14, 0x8c00
	s_nop 0
	global_load_lds_dwordx4 v160, s[12:13]
	s_add_u32 s12, s12, 0x80
	s_addc_u32 s13, s13, 0
	s_add_u32 s18, s18, 0x80
	s_addc_u32 s19, s19, 0
	s_mov_b32 s14, s28
	s_mov_b32 s11, s29
	v_add_u32_e32 v0, s14, v183
	ds_read_b128 v[186:189], v0
	ds_read_b128 v[190:193], v0 offset:4096
	ds_read_b128 v[194:197], v0 offset:8192
	ds_read_b128 v[198:201], v0 offset:12288
	v_add_u32_e32 v0, s11, v183
	ds_read_b128 v[202:205], v0 offset:32768
	ds_read_b128 v[206:209], v0 offset:36864
	v_add_u32_e32 v0, s14, v182
	ds_read_b128 v[210:213], v0
	ds_read_b128 v[214:217], v0 offset:4096
	ds_read_b128 v[218:221], v0 offset:8192
	ds_read_b128 v[222:225], v0 offset:12288
	v_add_u32_e32 v0, s11, v182
	ds_read_b128 v[226:229], v0 offset:32768
	ds_read_b128 v[250:253], v0 offset:36864
.Lrot5_loop:
	s_setprio 1
	s_waitcnt lgkmcnt(6)
	v_mfma_f32_32x32x16_bf16 v[114:129], v[186:189], v[202:205], v[114:129]
	v_mfma_f32_32x32x16_bf16 v[98:113], v[186:189], v[206:209], v[98:113]
	v_mfma_f32_32x32x16_bf16 v[82:97], v[190:193], v[202:205], v[82:97]
	v_mfma_f32_32x32x16_bf16 v[66:81], v[190:193], v[206:209], v[66:81]
	v_mfma_f32_32x32x16_bf16 v[50:65], v[194:197], v[202:205], v[50:65]
	v_mfma_f32_32x32x16_bf16 v[34:49], v[194:197], v[206:209], v[34:49]
	v_mfma_f32_32x32x16_bf16 v[18:33], v[198:201], v[202:205], v[18:33]
	v_mfma_f32_32x32x16_bf16 v[2:17], v[198:201], v[206:209], v[2:17]
	s_setprio 0
	v_add_u32_e32 v0, s14, v175
	ds_read_b128 v[186:189], v0
	ds_read_b128 v[190:193], v0 offset:4096
	ds_read_b128 v[194:197], v0 offset:8192
	ds_read_b128 v[198:201], v0 offset:12288
	v_add_u32_e32 v0, s11, v175
	ds_read_b128 v[202:205], v0 offset:32768
	ds_read_b128 v[206:209], v0 offset:36864
	s_setprio 1
	s_waitcnt lgkmcnt(6)
	v_mfma_f32_32x32x16_bf16 v[114:129], v[210:213], v[226:229], v[114:129]
	v_mfma_f32_32x32x16_bf16 v[98:113], v[210:213], v[250:253], v[98:113]
	v_mfma_f32_32x32x16_bf16 v[82:97], v[214:217], v[226:229], v[82:97]
	v_mfma_f32_32x32x16_bf16 v[66:81], v[214:217], v[250:253], v[66:81]
	v_mfma_f32_32x32x16_bf16 v[50:65], v[218:221], v[226:229], v[50:65]
	v_mfma_f32_32x32x16_bf16 v[34:49], v[218:221], v[250:253], v[34:49]
	v_mfma_f32_32x32x16_bf16 v[18:33], v[222:225], v[226:229], v[18:33]
	v_mfma_f32_32x32x16_bf16 v[2:17], v[222:225], v[250:253], v[2:17]
	s_setprio 0
	v_add_u32_e32 v0, s14, v172
	ds_read_b128 v[210:213], v0
	ds_read_b128 v[214:217], v0 offset:4096
	ds_read_b128 v[218:221], v0 offset:8192
	ds_read_b128 v[222:225], v0 offset:12288
	v_add_u32_e32 v0, s11, v172
	ds_read_b128 v[226:229], v0 offset:32768
	ds_read_b128 v[250:253], v0 offset:36864
	s_add_i32 s9, s9, 0x10000
	s_and_b32 s14, s9, 0x10000
	s_add_i32 s11, s14, s29
	s_add_i32 s14, s14, s28
	s_cmp_eq_u32 s9, 0xf0000
	s_waitcnt vmcnt(0) lgkmcnt(0)
	s_barrier
	s_cbranch_scc1 .Lrot5_tail
	s_setprio 1
	s_add_i32 m0, s9, 0x10000
	s_and_b32 m0, m0, 0x10000
	s_add_i32 m0, m0, s27
	v_mfma_f32_32x32x16_bf16 v[114:129], v[186:189], v[202:205], v[114:129]
	global_load_lds_dwordx4 v180, s[18:19]
	s_add_i32 m0, m0, 0x400
	v_mfma_f32_32x32x16_bf16 v[98:113], v[186:189], v[206:209], v[98:113]
	v_mfma_f32_32x32x16_bf16 v[82:97], v[190:193], v[202:205], v[82:97]
	global_load_lds_dwordx4 v178, s[18:19]
	s_add_i32 m0, m0, 0x400
	v_mfma_f32_32x32x16_bf16 v[66:81], v[190:193], v[206:209], v[66:81]
	v_mfma_f32_32x32x16_bf16 v[50:65], v[194:197], v[202:205], v[50:65]
	global_load_lds_dwordx4 v176, s[18:19]
	s_add_i32 m0, m0, 0x400
	v_mfma_f32_32x32x16_bf16 v[34:49], v[194:197], v[206:209], v[34:49]
	v_mfma_f32_32x32x16_bf16 v[18:33], v[198:201], v[202:205], v[18:33]
	global_load_lds_dwordx4 v168, s[18:19]
	s_add_i32 m0, m0, 0x7400
	v_mfma_f32_32x32x16_bf16 v[2:17], v[198:201], v[206:209], v[2:17]
	s_setprio 0
	v_add_u32_e32 v0, s14, v183
	ds_read_b128 v[186:189], v0
	ds_read_b128 v[190:193], v0 offset:4096
	ds_read_b128 v[194:197], v0 offset:8192
	ds_read_b128 v[198:201], v0 offset:12288
	v_add_u32_e32 v0, s11, v183
	ds_read_b128 v[202:205], v0 offset:32768
	ds_read_b128 v[206:209], v0 offset:36864
	s_setprio 1
	v_mfma_f32_32x32x16_bf16 v[114:129], v[210:213], v[226:229], v[114:129]
	global_load_lds_dwordx4 v166, s[12:13]
	s_add_i32 m0, m0, 0x400
	v_mfma_f32_32x32x16_bf16 v[98:113], v[210:213], v[250:253], v[98:113]
	v_mfma_f32_32x32x16_bf16 v[82:97], v[214:217], v[226:229], v[82:97]
	global_load_lds_dwordx4 v164, s[12:13]
	s_add_i32 m0, m0, 0x400
	v_mfma_f32_32x32x16_bf16 v[66:81], v[214:217], v[250:253], v[66:81]
	v_mfma_f32_32x32x16_bf16 v[50:65], v[218:221], v[226:229], v[50:65]
	global_load_lds_dwordx4 v162, s[12:13]
	s_add_i32 m0, m0, 0x400
	v_mfma_f32_32x32x16_bf16 v[34:49], v[218:221], v[250:253], v[34:49]
	v_mfma_f32_32x32x16_bf16 v[18:33], v[222:225], v[226:229], v[18:33]
	global_load_lds_dwordx4 v160, s[12:13]
	v_mfma_f32_32x32x16_bf16 v[2:17], v[222:225], v[250:253], v[2:17]
	s_setprio 0
	v_add_u32_e32 v0, s14, v182
	ds_read_b128 v[210:213], v0
	ds_read_b128 v[214:217], v0 offset:4096
	ds_read_b128 v[218:221], v0 offset:8192
	ds_read_b128 v[222:225], v0 offset:12288
	v_add_u32_e32 v0, s11, v182
	ds_read_b128 v[226:229], v0 offset:32768
	ds_read_b128 v[250:253], v0 offset:36864
	s_add_u32 s12, s12, 0x80
	s_addc_u32 s13, s13, 0
	s_add_u32 s18, s18, 0x80
	s_addc_u32 s19, s19, 0
	s_branch .Lrot5_loop

; #define MFMA32(a, b, c) __builtin_amdgcn_mfma_f32_32x32x16_bf16((a), (b), (c), 0, 0, 0)
; template <class AL, class EP>
; DI void gemm2(const int wave_s, const AL al, const u16* __restrict__ Wt, const int K, const int ntm, const int ntn, const EP ep, char* smem, const u16* zrow = nullptr) {
;     ...
;     auto stage_issue = [&](int kt, int st) {
;       char* sa = smem + st * G_STAGE_B + wv * 4096;
;       const int k0 = kt * 64;
;       if constexpr (AL::DIRECT) {
;         const u16* ab = al.tilebase(tm, k0);
; #pragma unroll
;         for (int q = 0; q < 4; ++q) {
;           const u16* gp = (aoff[q] == 0xffffffffu) ? (zrow + scp * 8) : (ab + aoff[q]);
;           glds16(gp, sa + q * 1024);
;         }
;       } else {
; #pragma unroll
;         for (int i = 0; i < 4; ++i) ra[i] = al.load(tm, lrow + 64 * i, k0, lcp * 8);
;       }
;       const u16* wb = wbase + k0;
; #pragma unroll
;       for (int q = 0; q < 4; ++q) glds16(wb + woff[q], sa + 32768 + q * 1024);
;     ...
;     for (int kt = 0; kt < nk; ++kt) {
;       const bool more = (kt + 1 < nk);
;       if (more) stage_issue(kt + 1, (kt + 1) & 1);
;       __builtin_amdgcn_sched_barrier(0);
;       const char* a = smem + (kt & 1) * G_STAGE_B + wm * 128 * 128;
;       const char* b = smem + (kt & 1) * G_STAGE_B + 32768 + wn * 64 * 128;
;       if constexpr (AL::DIRECT) {
;         bf16x8 af[2][4], bfr[2][2];
; #pragma unroll
;         for (int i = 0; i < 4; ++i) af[0][i] = *(const bf16x8*)(a + i * 4096 + foff[0]);
; #pragma unroll
;         for (int j = 0; j < 2; ++j) bfr[0][j] = *(const bf16x8*)(b + j * 4096 + foff[0]);
; #pragma unroll
;         for (int s = 0; s < 4; ++s) {
;           if (s < 3) {
; #pragma unroll
;             for (int i = 0; i < 4; ++i) af[(s + 1) & 1][i] = *(const bf16x8*)(a + i * 4096 + foff[s + 1]);
; #pragma unroll
;             for (int j = 0; j < 2; ++j) bfr[(s + 1) & 1][j] = *(const bf16x8*)(b + j * 4096 + foff[s + 1]);
;           }
;           __builtin_amdgcn_sched_barrier(0);
;           __builtin_amdgcn_s_setprio(1);
; #pragma unroll
;           for (int i = 0; i < 4; ++i) {
;             acc[i][0] = MFMA32(af[s & 1][i], bfr[s & 1][0], acc[i][0]);
;             acc[i][1] = MFMA32(af[s & 1][i], bfr[s & 1][1], acc[i][1]);
;           }
;           __builtin_amdgcn_s_setprio(0);
;           __builtin_amdgcn_sched_barrier(0);
;         }
.LBB0_3321:
	s_add_u32 s8, s14, 0x80
	s_addc_u32 s9, s15, 0
	s_add_u32 s30, s30, 0x80
	s_addc_u32 s31, s31, 0
	v_subrev_u32_e32 v176, s30, v176
	v_subrev_u32_e32 v168, s30, v168
	v_subrev_u32_e32 v166, s30, v166
	v_subrev_u32_e32 v164, s30, v164
	v_subrev_u32_e32 v162, s8, v162
	v_subrev_u32_e32 v160, s8, v160
	v_subrev_u32_e32 v158, s8, v158
	v_subrev_u32_e32 v156, s8, v156
	s_add_i32 s14, s17, 0x10000
	s_mov_b32 m0, s14
	s_nop 0
	global_load_lds_dwordx4 v176, s[30:31]
	s_add_i32 m0, s14, 0x400
	s_nop 0
	global_load_lds_dwordx4 v168, s[30:31]
	s_add_i32 m0, s14, 0x800
	s_nop 0
	global_load_lds_dwordx4 v166, s[30:31]
	s_add_i32 m0, s14, 0xc00
	s_nop 0
	global_load_lds_dwordx4 v164, s[30:31]
	s_add_i32 m0, s14, 0x8000
	s_nop 0
	global_load_lds_dwordx4 v162, s[8:9]
	s_add_i32 m0, s14, 0x8400
	s_nop 0
	global_load_lds_dwordx4 v160, s[8:9]
	s_add_i32 m0, s14, 0x8800
	s_nop 0
	global_load_lds_dwordx4 v158, s[8:9]
	s_add_i32 m0, s14, 0x8c00
	s_nop 0
	global_load_lds_dwordx4 v156, s[8:9]
	s_add_u32 s8, s8, 0x80
	s_addc_u32 s9, s9, 0
	s_add_u32 s30, s30, 0x80
	s_addc_u32 s31, s31, 0
	s_mov_b32 s14, s18
	s_mov_b32 s7, s19
	v_add_u32_e32 v181, s14, v178
	ds_read_b128 v[182:185], v181
	ds_read_b128 v[186:189], v181 offset:4096
	ds_read_b128 v[190:193], v181 offset:8192
	ds_read_b128 v[194:197], v181 offset:12288
	v_add_u32_e32 v181, s7, v178
	ds_read_b128 v[198:201], v181 offset:32768
	ds_read_b128 v[202:205], v181 offset:36864
	v_add_u32_e32 v181, s14, v175
	ds_read_b128 v[206:209], v181
	ds_read_b128 v[210:213], v181 offset:4096
	ds_read_b128 v[214:217], v181 offset:8192
	ds_read_b128 v[218:221], v181 offset:12288
	v_add_u32_e32 v181, s7, v175
	ds_read_b128 v[222:225], v181 offset:32768
	ds_read_b128 v[226:229], v181 offset:36864
.Lrot6_loop:
	s_setprio 1
	s_waitcnt lgkmcnt(6)
	v_mfma_f32_32x32x16_bf16 v[114:129], v[182:185], v[198:201], v[114:129]
	v_mfma_f32_32x32x16_bf16 v[98:113], v[182:185], v[202:205], v[98:113]
	v_mfma_f32_32x32x16_bf16 v[82:97], v[186:189], v[198:201], v[82:97]
	v_mfma_f32_32x32x16_bf16 v[66:81], v[186:189], v[202:205], v[66:81]
	v_mfma_f32_32x32x16_bf16 v[50:65], v[190:193], v[198:201], v[50:65]
	v_mfma_f32_32x32x16_bf16 v[34:49], v[190:193], v[202:205], v[34:49]
	v_mfma_f32_32x32x16_bf16 v[18:33], v[194:197], v[198:201], v[18:33]
	v_mfma_f32_32x32x16_bf16 v[2:17], v[194:197], v[202:205], v[2:17]
	s_setprio 0
	v_add_u32_e32 v181, s14, v172
	ds_read_b128 v[182:185], v181
	ds_read_b128 v[186:189], v181 offset:4096
	ds_read_b128 v[190:193], v181 offset:8192
	ds_read_b128 v[194:197], v181 offset:12288
	v_add_u32_e32 v181, s7, v172
	ds_read_b128 v[198:201], v181 offset:32768
	ds_read_b128 v[202:205], v181 offset:36864
	s_setprio 1
	s_waitcnt lgkmcnt(6)
	v_mfma_f32_32x32x16_bf16 v[114:129], v[206:209], v[222:225], v[114:129]
	v_mfma_f32_32x32x16_bf16 v[98:113], v[206:209], v[226:229], v[98:113]
	v_mfma_f32_32x32x16_bf16 v[82:97], v[210:213], v[222:225], v[82:97]
	v_mfma_f32_32x32x16_bf16 v[66:81], v[210:213], v[226:229], v[66:81]
	v_mfma_f32_32x32x16_bf16 v[50:65], v[214:217], v[222:225], v[50:65]
	v_mfma_f32_32x32x16_bf16 v[34:49], v[214:217], v[226:229], v[34:49]
	v_mfma_f32_32x32x16_bf16 v[18:33], v[218:221], v[222:225], v[18:33]
	v_mfma_f32_32x32x16_bf16 v[2:17], v[218:221], v[226:229], v[2:17]
	s_setprio 0
	v_add_u32_e32 v181, s14, v0
	ds_read_b128 v[206:209], v181
	ds_read_b128 v[210:213], v181 offset:4096
	ds_read_b128 v[214:217], v181 offset:8192
	ds_read_b128 v[218:221], v181 offset:12288
	v_add_u32_e32 v181, s7, v0
	ds_read_b128 v[222:225], v181 offset:32768
	ds_read_b128 v[226:229], v181 offset:36864
	s_add_i32 s5, s5, 0x10000
	s_and_b32 s14, s5, 0x10000
	s_add_i32 s7, s14, s19
	s_add_i32 s14, s14, s18
	s_cmp_eq_u32 s5, 0xf0000
	s_waitcnt vmcnt(0) lgkmcnt(0)
	s_barrier
	s_cbranch_scc1 .Lrot6_tail
	s_setprio 1
	s_add_i32 m0, s5, 0x10000
	s_and_b32 m0, m0, 0x10000
	s_add_i32 m0, m0, s17
	v_mfma_f32_32x32x16_bf16 v[114:129], v[182:185], v[198:201], v[114:129]
	global_load_lds_dwordx4 v176, s[30:31]
	s_add_i32 m0, m0, 0x400
	v_mfma_f32_32x32x16_bf16 v[98:113], v[182:185], v[202:205], v[98:113]
	v_mfma_f32_32x32x16_bf16 v[82:97], v[186:189], v[198:201], v[82:97]
	global_load_lds_dwordx4 v168, s[30:31]
	s_add_i32 m0, m0, 0x400
	v_mfma_f32_32x32x16_bf16 v[66:81], v[186:189], v[202:205], v[66:81]
	v_mfma_f32_32x32x16_bf16 v[50:65], v[190:193], v[198:201], v[50:65]
	global_load_lds_dwordx4 v166, s[30:31]
	s_add_i32 m0, m0, 0x400
	v_mfma_f32_32x32x16_bf16 v[34:49], v[190:193], v[202:205], v[34:49]
	v_mfma_f32_32x32x16_bf16 v[18:33], v[194:197], v[198:201], v[18:33]
	global_load_lds_dwordx4 v164, s[30:31]
	s_add_i32 m0, m0, 0x7400
	v_mfma_f32_32x32x16_bf16 v[2:17], v[194:197], v[202:205], v[2:17]
	s_setprio 0
	v_add_u32_e32 v181, s14, v178
	ds_read_b128 v[182:185], v181
	ds_read_b128 v[186:189], v181 offset:4096
	ds_read_b128 v[190:193], v181 offset:8192
	ds_read_b128 v[194:197], v181 offset:12288
	v_add_u32_e32 v181, s7, v178
	ds_read_b128 v[198:201], v181 offset:32768
	ds_read_b128 v[202:205], v181 offset:36864
	s_setprio 1
	v_mfma_f32_32x32x16_bf16 v[114:129], v[206:209], v[222:225], v[114:129]
	global_load_lds_dwordx4 v162, s[8:9]
	s_add_i32 m0, m0, 0x400
	v_mfma_f32_32x32x16_bf16 v[98:113], v[206:209], v[226:229], v[98:113]
	v_mfma_f32_32x32x16_bf16 v[82:97], v[210:213], v[222:225], v[82:97]
	global_load_lds_dwordx4 v160, s[8:9]
	s_add_i32 m0, m0, 0x400
	v_mfma_f32_32x32x16_bf16 v[66:81], v[210:213], v[226:229], v[66:81]
	v_mfma_f32_32x32x16_bf16 v[50:65], v[214:217], v[222:225], v[50:65]
	global_load_lds_dwordx4 v158, s[8:9]
	s_add_i32 m0, m0, 0x400
	v_mfma_f32_32x32x16_bf16 v[34:49], v[214:217], v[226:229], v[34:49]
	v_mfma_f32_32x32x16_bf16 v[18:33], v[218:221], v[222:225], v[18:33]
	global_load_lds_dwordx4 v156, s[8:9]
	v_mfma_f32_32x32x16_bf16 v[2:17], v[218:221], v[226:229], v[2:17]
	s_setprio 0
	v_add_u32_e32 v181, s14, v175
	ds_read_b128 v[206:209], v181
	ds_read_b128 v[210:213], v181 offset:4096
	ds_read_b128 v[214:217], v181 offset:8192
	ds_read_b128 v[218:221], v181 offset:12288
	v_add_u32_e32 v181, s7, v175
	ds_read_b128 v[222:225], v181 offset:32768
	ds_read_b128 v[226:229], v181 offset:36864
	s_add_u32 s8, s8, 0x80
	s_addc_u32 s9, s9, 0
	s_add_u32 s30, s30, 0x80
	s_addc_u32 s31, s31, 0
	s_branch .Lrot6_loop

; #define MFMA32(a, b, c) __builtin_amdgcn_mfma_f32_32x32x16_bf16((a), (b), (c), 0, 0, 0)
; template <class AL, class EP>
; DI void gemm2(const int wave_s, const AL al, const u16* __restrict__ Wt, const int K, const int ntm, const int ntn, const EP ep, char* smem, const u16* zrow = nullptr) {
;     ...
;     auto stage_issue = [&](int kt, int st) {
;       char* sa = smem + st * G_STAGE_B + wv * 4096;
;       const int k0 = kt * 64;
;       if constexpr (AL::DIRECT) {
;         const u16* ab = al.tilebase(tm, k0);
; #pragma unroll
;         for (int q = 0; q < 4; ++q) {
;           const u16* gp = (aoff[q] == 0xffffffffu) ? (zrow + scp * 8) : (ab + aoff[q]);
;           glds16(gp, sa + q * 1024);
;         }
;       } else {
; #pragma unroll
;         for (int i = 0; i < 4; ++i) ra[i] = al.load(tm, lrow + 64 * i, k0, lcp * 8);
;       }
;       const u16* wb = wbase + k0;
; #pragma unroll
;       for (int q = 0; q < 4; ++q) glds16(wb + woff[q], sa + 32768 + q * 1024);
;     ...
;     for (int kt = 0; kt < nk; ++kt) {
;       const bool more = (kt + 1 < nk);
;       if (more) stage_issue(kt + 1, (kt + 1) & 1);
;       __builtin_amdgcn_sched_barrier(0);
;       const char* a = smem + (kt & 1) * G_STAGE_B + wm * 128 * 128;
;       const char* b = smem + (kt & 1) * G_STAGE_B + 32768 + wn * 64 * 128;
;       if constexpr (AL::DIRECT) {
;         bf16x8 af[2][4], bfr[2][2];
; #pragma unroll
;         for (int i = 0; i < 4; ++i) af[0][i] = *(const bf16x8*)(a + i * 4096 + foff[0]);
; #pragma unroll
;         for (int j = 0; j < 2; ++j) bfr[0][j] = *(const bf16x8*)(b + j * 4096 + foff[0]);
; #pragma unroll
;         for (int s = 0; s < 4; ++s) {
;           if (s < 3) {
; #pragma unroll
;             for (int i = 0; i < 4; ++i) af[(s + 1) & 1][i] = *(const bf16x8*)(a + i * 4096 + foff[s + 1]);
; #pragma unroll
;             for (int j = 0; j < 2; ++j) bfr[(s + 1) & 1][j] = *(const bf16x8*)(b + j * 4096 + foff[s + 1]);
;           }
;           __builtin_amdgcn_sched_barrier(0);
;           __builtin_amdgcn_s_setprio(1);
; #pragma unroll
;           for (int i = 0; i < 4; ++i) {
;             acc[i][0] = MFMA32(af[s & 1][i], bfr[s & 1][0], acc[i][0]);
;             acc[i][1] = MFMA32(af[s & 1][i], bfr[s & 1][1], acc[i][1]);
;           }
;           __builtin_amdgcn_s_setprio(0);
;           __builtin_amdgcn_sched_barrier(0);
;         }
.LBB0_3455:
	s_add_u32 s16, s18, 0x80
	s_addc_u32 s17, s19, 0
	s_add_u32 s38, s38, 0x80
	s_addc_u32 s39, s39, 0
	v_subrev_u32_e32 v176, s38, v176
	v_subrev_u32_e32 v168, s38, v168
	v_subrev_u32_e32 v166, s38, v166
	v_subrev_u32_e32 v164, s38, v164
	v_subrev_u32_e32 v162, s16, v162
	v_subrev_u32_e32 v160, s16, v160
	v_subrev_u32_e32 v158, s16, v158
	v_subrev_u32_e32 v156, s16, v156
	s_add_i32 s18, s23, 0x10000
	s_mov_b32 m0, s18
	s_nop 0
	global_load_lds_dwordx4 v176, s[38:39]
	s_add_i32 m0, s18, 0x400
	s_nop 0
	global_load_lds_dwordx4 v168, s[38:39]
	s_add_i32 m0, s18, 0x800
	s_nop 0
	global_load_lds_dwordx4 v166, s[38:39]
	s_add_i32 m0, s18, 0xc00
	s_nop 0
	global_load_lds_dwordx4 v164, s[38:39]
	s_add_i32 m0, s18, 0x8000
	s_nop 0
	global_load_lds_dwordx4 v162, s[16:17]
	s_add_i32 m0, s18, 0x8400
	s_nop 0
	global_load_lds_dwordx4 v160, s[16:17]
	s_add_i32 m0, s18, 0x8800
	s_nop 0
	global_load_lds_dwordx4 v158, s[16:17]
	s_add_i32 m0, s18, 0x8c00
	s_nop 0
	global_load_lds_dwordx4 v156, s[16:17]
	s_add_u32 s16, s16, 0x80
	s_addc_u32 s17, s17, 0
	s_add_u32 s38, s38, 0x80
	s_addc_u32 s39, s39, 0
	s_mov_b32 s18, s24
	s_mov_b32 s7, s25
	v_add_u32_e32 v181, s18, v178
	ds_read_b128 v[182:185], v181
	ds_read_b128 v[186:189], v181 offset:4096
	ds_read_b128 v[190:193], v181 offset:8192
	ds_read_b128 v[194:197], v181 offset:12288
	v_add_u32_e32 v181, s7, v178
	ds_read_b128 v[198:201], v181 offset:32768
	ds_read_b128 v[202:205], v181 offset:36864
	v_add_u32_e32 v181, s18, v175
	ds_read_b128 v[206:209], v181
	ds_read_b128 v[210:213], v181 offset:4096
	ds_read_b128 v[214:217], v181 offset:8192
	ds_read_b128 v[218:221], v181 offset:12288
	v_add_u32_e32 v181, s7, v175
	ds_read_b128 v[222:225], v181 offset:32768
	ds_read_b128 v[226:229], v181 offset:36864
.Lrot7_loop:
	s_setprio 1
	s_waitcnt lgkmcnt(6)
	v_mfma_f32_32x32x16_bf16 v[114:129], v[182:185], v[198:201], v[114:129]
	v_mfma_f32_32x32x16_bf16 v[98:113], v[182:185], v[202:205], v[98:113]
	v_mfma_f32_32x32x16_bf16 v[82:97], v[186:189], v[198:201], v[82:97]
	v_mfma_f32_32x32x16_bf16 v[66:81], v[186:189], v[202:205], v[66:81]
	v_mfma_f32_32x32x16_bf16 v[50:65], v[190:193], v[198:201], v[50:65]
	v_mfma_f32_32x32x16_bf16 v[34:49], v[190:193], v[202:205], v[34:49]
	v_mfma_f32_32x32x16_bf16 v[18:33], v[194:197], v[198:201], v[18:33]
	v_mfma_f32_32x32x16_bf16 v[2:17], v[194:197], v[202:205], v[2:17]
	s_setprio 0
	v_add_u32_e32 v181, s18, v172
	ds_read_b128 v[182:185], v181
	ds_read_b128 v[186:189], v181 offset:4096
	ds_read_b128 v[190:193], v181 offset:8192
	ds_read_b128 v[194:197], v181 offset:12288
	v_add_u32_e32 v181, s7, v172
	ds_read_b128 v[198:201], v181 offset:32768
	ds_read_b128 v[202:205], v181 offset:36864
	s_setprio 1
	s_waitcnt lgkmcnt(6)
	v_mfma_f32_32x32x16_bf16 v[114:129], v[206:209], v[222:225], v[114:129]
	v_mfma_f32_32x32x16_bf16 v[98:113], v[206:209], v[226:229], v[98:113]
	v_mfma_f32_32x32x16_bf16 v[82:97], v[210:213], v[222:225], v[82:97]
	v_mfma_f32_32x32x16_bf16 v[66:81], v[210:213], v[226:229], v[66:81]
	v_mfma_f32_32x32x16_bf16 v[50:65], v[214:217], v[222:225], v[50:65]
	v_mfma_f32_32x32x16_bf16 v[34:49], v[214:217], v[226:229], v[34:49]
	v_mfma_f32_32x32x16_bf16 v[18:33], v[218:221], v[222:225], v[18:33]
	v_mfma_f32_32x32x16_bf16 v[2:17], v[218:221], v[226:229], v[2:17]
	s_setprio 0
	v_add_u32_e32 v181, s18, v0
	ds_read_b128 v[206:209], v181
	ds_read_b128 v[210:213], v181 offset:4096
	ds_read_b128 v[214:217], v181 offset:8192
	ds_read_b128 v[218:221], v181 offset:12288
	v_add_u32_e32 v181, s7, v0
	ds_read_b128 v[222:225], v181 offset:32768
	ds_read_b128 v[226:229], v181 offset:36864
	s_add_i32 s5, s5, 0x10000
	s_and_b32 s18, s5, 0x10000
	s_add_i32 s7, s18, s25
	s_add_i32 s18, s18, s24
	s_cmp_eq_u32 s5, 0x70000
	s_waitcnt vmcnt(0) lgkmcnt(0)
	s_barrier
	s_cbranch_scc1 .Lrot7_tail
	s_setprio 1
	s_add_i32 m0, s5, 0x10000
	s_and_b32 m0, m0, 0x10000
	s_add_i32 m0, m0, s23
	v_mfma_f32_32x32x16_bf16 v[114:129], v[182:185], v[198:201], v[114:129]
	global_load_lds_dwordx4 v176, s[38:39]
	s_add_i32 m0, m0, 0x400
	v_mfma_f32_32x32x16_bf16 v[98:113], v[182:185], v[202:205], v[98:113]
	v_mfma_f32_32x32x16_bf16 v[82:97], v[186:189], v[198:201], v[82:97]
	global_load_lds_dwordx4 v168, s[38:39]
	s_add_i32 m0, m0, 0x400
	v_mfma_f32_32x32x16_bf16 v[66:81], v[186:189], v[202:205], v[66:81]
	v_mfma_f32_32x32x16_bf16 v[50:65], v[190:193], v[198:201], v[50:65]
	global_load_lds_dwordx4 v166, s[38:39]
	s_add_i32 m0, m0, 0x400
	v_mfma_f32_32x32x16_bf16 v[34:49], v[190:193], v[202:205], v[34:49]
	v_mfma_f32_32x32x16_bf16 v[18:33], v[194:197], v[198:201], v[18:33]
	global_load_lds_dwordx4 v164, s[38:39]
	s_add_i32 m0, m0, 0x7400
	v_mfma_f32_32x32x16_bf16 v[2:17], v[194:197], v[202:205], v[2:17]
	s_setprio 0
	v_add_u32_e32 v181, s18, v178
	ds_read_b128 v[182:185], v181
	ds_read_b128 v[186:189], v181 offset:4096
	ds_read_b128 v[190:193], v181 offset:8192
	ds_read_b128 v[194:197], v181 offset:12288
	v_add_u32_e32 v181, s7, v178
	ds_read_b128 v[198:201], v181 offset:32768
	ds_read_b128 v[202:205], v181 offset:36864
	s_setprio 1
	v_mfma_f32_32x32x16_bf16 v[114:129], v[206:209], v[222:225], v[114:129]
	global_load_lds_dwordx4 v162, s[16:17]
	s_add_i32 m0, m0, 0x400
	v_mfma_f32_32x32x16_bf16 v[98:113], v[206:209], v[226:229], v[98:113]
	v_mfma_f32_32x32x16_bf16 v[82:97], v[210:213], v[222:225], v[82:97]
	global_load_lds_dwordx4 v160, s[16:17]
	s_add_i32 m0, m0, 0x400
	v_mfma_f32_32x32x16_bf16 v[66:81], v[210:213], v[226:229], v[66:81]
	v_mfma_f32_32x32x16_bf16 v[50:65], v[214:217], v[222:225], v[50:65]
	global_load_lds_dwordx4 v158, s[16:17]
	s_add_i32 m0, m0, 0x400
	v_mfma_f32_32x32x16_bf16 v[34:49], v[214:217], v[226:229], v[34:49]
	v_mfma_f32_32x32x16_bf16 v[18:33], v[218:221], v[222:225], v[18:33]
	global_load_lds_dwordx4 v156, s[16:17]
	v_mfma_f32_32x32x16_bf16 v[2:17], v[218:221], v[226:229], v[2:17]
	s_setprio 0
	v_add_u32_e32 v181, s18, v175
	ds_read_b128 v[206:209], v181
	ds_read_b128 v[210:213], v181 offset:4096
	ds_read_b128 v[214:217], v181 offset:8192
	ds_read_b128 v[218:221], v181 offset:12288
	v_add_u32_e32 v181, s7, v175
	ds_read_b128 v[222:225], v181 offset:32768
	ds_read_b128 v[226:229], v181 offset:36864
	s_add_u32 s16, s16, 0x80
	s_addc_u32 s17, s17, 0
	s_add_u32 s38, s38, 0x80
	s_addc_u32 s39, s39, 0
	s_branch .Lrot7_loop
